# MoE down epilogue: bf16 rows transposed through an idle 16KB LDS stage buffer (XOR swizzle), stores are 2 rows x 512 contiguous bytes instead of 16 rows x 64B
# speedup vs baseline: 1.0096x; 1.0096x over previous
; #define LAS __attribute__((address_space(3)))
; __device__ __forceinline__ unsigned cvt_pk_bf16(float lo, float hi) { unsigned r; asm("v_cvt_pk_bf16_f32 %0, %1, %2" : "=v"(r) : "v"(lo), "v"(hi)); return r; }
;     __device__ __forceinline__ void operator()(const f32x4 (&acc)[2][2][4][2], const pg8::Unit& u, int wr, int wc, int fr, int fq, LAS unsigned char* lds) const {
;         const LAS int* SL = (const LAS int*)(lds + SB_OFF) + 64 * wr + fr; const LAS float* GW = (const LAS float*)(lds + SB_OFF + 1024) + 64 * wr + fr;
;         const LAS float* BI = (const LAS float*)(lds + SB_OFF + 2048) + 32 * wc + 8 * fq;
;         int slot[2][4]; float gw[2][4];
; #pragma unroll
;         for (int ai = 0; ai < 2; ++ai)
; #pragma unroll
;             for (int m = 0; m < 4; ++m) { slot[ai][m] = SL[128 * ai + 16 * m]; gw[ai][m] = GW[128 * ai + 16 * m]; }
;         f32x4 bv[2][2];
; #pragma unroll
;         for (int bj = 0; bj < 2; ++bj)
; #pragma unroll
;             for (int n = 0; n < 2; ++n) bv[bj][n] = *(const LAS f32x4*)(BI + 128 * bj + 4 * n);
; #pragma unroll
;         for (int ai = 0; ai < 2; ++ai)
; #pragma unroll
;             for (int m = 0; m < 4; ++m) { const int r = 128 * ai + 64 * wr + 16 * m + fr; if (r >= u.nvalid) continue;
; #pragma unroll
;                 for (int bj = 0; bj < 2; ++bj) { const int col = 256 * u.pn + 128 * bj + 32 * wc + 8 * fq;
;                     const f32x4 v0 = (acc[ai][bj][m][0] * dq + bv[bj][0]) * gw[ai][m], v1 = (acc[ai][bj][m][1] * dq + bv[bj][1]) * gw[ai][m];
;                     u32x4 o; o.x = cvt_pk_bf16(v0.x, v0.y); o.y = cvt_pk_bf16(v0.z, v0.w); o.z = cvt_pk_bf16(v1.x, v1.y); o.w = cvt_pk_bf16(v1.z, v1.w);
;                     *(u32x4*)(YK + (size_t)slot[ai][m] * D + col) = o; } }
;     }
.LBB0_2347:
	v_and_b32_e32 v239, 63, v0
	v_lshrrev_b32_e32 v240, 5, v239
	v_and_b32_e32 v241, 31, v239
	s_lshr_b32 s26, s66, 3
	v_add_u32_e32 v242, s26, v240
	s_lshl_b32 s27, s65, 7
	s_add_i32 s27, s27, 0xc000
	v_and_b32_e32 v243, 7, v242
	v_xor_b32_e32 v243, v243, v241
	v_lshlrev_b32_e32 v243, 4, v243
	v_lshl_add_u32 v243, v242, 9, v243
	v_add_u32_e32 v243, s27, v243
	v_add_u32_e32 v244, 2, v242
	v_and_b32_e32 v245, 7, v244
	v_xor_b32_e32 v245, v245, v241
	v_lshlrev_b32_e32 v245, 4, v245
	v_lshl_add_u32 v244, v244, 9, v245
	v_add_u32_e32 v244, s27, v244
	v_add_u32_e32 v245, s26, v211
	v_and_b32_e32 v246, 7, v210
	v_xor_b32_e32 v245, v245, v246
	v_lshlrev_b32_e32 v245, 4, v245
	v_lshl_add_u32 v245, v210, 9, v245
	v_add_u32_e32 v245, s27, v245
	v_add_u32_e32 v239, s65, v242
	v_lshlrev_b32_e32 v246, 2, v239
	s_add_i32 s27, s4, 0x22400
	v_add_u32_e32 v246, s27, v246
	v_lshlrev_b32_e32 v240, 4, v241
	s_lshl_b32 s26, s54, 9
	v_add_u32_e32 v240, s26, v240
	v_mov_b32_e32 v241, 0
	v_lshl_add_u64 v[240:241], s[42:43], 0, v[240:241]
	v_mov_b32_e32 v19, v210
	v_mov_b32_e32 v22, v211
	s_lshl_b32 s26, s65, 2
	s_add_i32 s5, s5, s26
	v_lshlrev_b32_e32 v2, 2, v19
	s_add_i32 s27, s4, s26
	v_add_u32_e32 v36, s5, v2
	s_lshl_b32 s5, s66, 2
	s_add_i32 s27, s27, 0x22400
	s_add_i32 s4, s4, s5
	v_add_u32_e32 v21, s27, v2
	v_lshl_add_u32 v2, v22, 5, s4
	v_add_u32_e32 v2, 0x22c00, v2
	ds_read2_b32 v[32:33], v21 offset0:16 offset1:32
	ds_read2_b32 v[34:35], v36 offset0:16 offset1:32
	ds_read2_b32 v[28:29], v21 offset0:48 offset1:128
	ds_read2_b32 v[30:31], v36 offset0:48 offset1:128
	ds_read2_b32 v[24:25], v21 offset0:144 offset1:160
	ds_read2_b32 v[26:27], v36 offset0:144 offset1:160
	ds_read_b32 v20, v21 offset:704
	ds_read_b32 v18, v36 offset:704
	ds_read_b128 v[14:17], v2
	ds_read_b128 v[10:13], v2 offset:16
	ds_read_b128 v[6:9], v2 offset:512
	ds_read_b128 v[2:5], v2 offset:528
	s_lshl_b32 s4, s54, 8
	s_or_b32 s4, s4, s66
	v_add_u32_e32 v19, s65, v19
	v_lshl_add_u32 v22, v22, 3, s4
	v_cmp_lt_i32_e32 vcc, v19, v207
	v_ashrrev_i32_e32 v23, 31, v22
	s_and_saveexec_b64 s[4:5], vcc
	s_cbranch_execz .LBB0_2349
	ds_read_b32 v40, v21
	ds_read_b32 v42, v36
	v_mov_b32_e32 v205, v204
	s_waitcnt lgkmcnt(0)
	v_pk_fma_f32 v[36:37], v[208:209], v[194:195], v[14:15]
	v_pk_fma_f32 v[38:39], v[204:205], v[196:197], v[16:17]
	v_ashrrev_i32_e32 v41, 31, v40
	v_lshlrev_b64 v[40:41], 11, v[40:41]
	v_pk_mul_f32 v[38:39], v[38:39], v[42:43] op_sel_hi:[1,0]
	v_pk_mul_f32 v[36:37], v[36:37], v[42:43] op_sel_hi:[1,0]
	v_pk_fma_f32 v[44:45], v[204:205], v[192:193], v[12:13]
	v_pk_fma_f32 v[46:47], v[208:209], v[190:191], v[10:11]
	v_lshl_add_u64 v[40:41], s[42:43], 0, v[40:41]
	v_pk_mul_f32 v[44:45], v[44:45], v[42:43] op_sel_hi:[1,0]
	v_pk_mul_f32 v[46:47], v[46:47], v[42:43] op_sel_hi:[1,0]
	v_cvt_pk_bf16_f32 v36, v36, v37
	v_cvt_pk_bf16_f32 v37, v38, v39
	v_cvt_pk_bf16_f32 v39, v44, v45
	v_lshl_add_u64 v[40:41], v[22:23], 1, v[40:41]
	v_cvt_pk_bf16_f32 v38, v46, v47
	ds_write_b128 v245, v[36:39]
	v_pk_fma_f32 v[46:47], v[208:209], v[182:183], v[2:3]
	s_nop 0
	v_pk_fma_f32 v[36:37], v[204:205], v[188:189], v[8:9]
	v_pk_fma_f32 v[38:39], v[208:209], v[186:187], v[6:7]
	v_pk_mul_f32 v[44:45], v[36:37], v[42:43] op_sel_hi:[1,0]
	v_pk_mul_f32 v[36:37], v[38:39], v[42:43] op_sel_hi:[1,0]
	v_pk_fma_f32 v[38:39], v[204:205], v[184:185], v[4:5]
	v_cvt_pk_bf16_f32 v36, v36, v37
	v_cvt_pk_bf16_f32 v37, v44, v45
	s_nop 0
	v_pk_mul_f32 v[48:49], v[38:39], v[42:43] op_sel_hi:[1,0]
	v_pk_mul_f32 v[38:39], v[46:47], v[42:43] op_sel_hi:[1,0]
	s_nop 0
	v_cvt_pk_bf16_f32 v38, v38, v39
	v_cvt_pk_bf16_f32 v39, v48, v49
	ds_write_b128 v245, v[36:39] offset:256
.LBB0_2349:
	s_or_b64 exec, exec, s[4:5]
	s_waitcnt lgkmcnt(0)
	s_barrier
	ds_read_b128 v[182:185], v243
	ds_read_b128 v[186:189], v244
	ds_read_b32 v190, v246
	ds_read_b32 v192, v246 offset:8
	s_waitcnt lgkmcnt(0)
	s_barrier
	v_add_u32_e32 v194, 0, v239
	v_cmp_lt_i32_e32 vcc, v194, v207
	s_and_saveexec_b64 s[4:5], vcc
	v_ashrrev_i32_e32 v191, 31, v190
	v_lshlrev_b64 v[190:191], 11, v[190:191]
	v_lshl_add_u64 v[190:191], v[240:241], 0, v[190:191]
	global_store_dwordx4 v[190:191], v[182:185], off
	s_or_b64 exec, exec, s[4:5]
	v_add_u32_e32 v194, 2, v239
	v_cmp_lt_i32_e32 vcc, v194, v207
	s_and_saveexec_b64 s[4:5], vcc
	v_ashrrev_i32_e32 v193, 31, v192
	v_lshlrev_b64 v[192:193], 11, v[192:193]
	v_lshl_add_u64 v[192:193], v[240:241], 0, v[192:193]
	global_store_dwordx4 v[192:193], v[186:189], off
	s_or_b64 exec, exec, s[4:5]
	v_add_u32_e32 v21, 16, v19
	v_cmp_lt_i32_e32 vcc, v21, v207
	s_and_saveexec_b64 s[4:5], vcc
	s_cbranch_execz .LBB0_2351
	v_mov_b32_e32 v205, v204
	s_waitcnt lgkmcnt(0)
	v_pk_fma_f32 v[36:37], v[204:205], v[180:181], v[16:17]
	v_pk_fma_f32 v[38:39], v[208:209], v[178:179], v[14:15]
	v_pk_mul_f32 v[40:41], v[34:35], v[36:37] op_sel_hi:[0,1]
	v_pk_mul_f32 v[36:37], v[34:35], v[38:39] op_sel_hi:[0,1]
	v_cvt_pk_bf16_f32 v36, v36, v37
	v_cvt_pk_bf16_f32 v37, v40, v41
	v_ashrrev_i32_e32 v41, 31, v32
	v_mov_b32_e32 v40, v32
	v_pk_fma_f32 v[38:39], v[204:205], v[176:177], v[12:13]
	v_pk_fma_f32 v[42:43], v[208:209], v[174:175], v[10:11]
	v_lshlrev_b64 v[40:41], 11, v[40:41]
	v_pk_mul_f32 v[44:45], v[34:35], v[38:39] op_sel_hi:[0,1]
	v_pk_mul_f32 v[38:39], v[34:35], v[42:43] op_sel_hi:[0,1]
	v_lshl_add_u64 v[40:41], s[42:43], 0, v[40:41]
	v_cvt_pk_bf16_f32 v38, v38, v39
	v_cvt_pk_bf16_f32 v39, v44, v45
	v_lshl_add_u64 v[40:41], v[22:23], 1, v[40:41]
	ds_write_b128 v245, v[36:39]
	v_pk_fma_f32 v[44:45], v[208:209], v[166:167], v[2:3]
	s_nop 0
	v_pk_fma_f32 v[36:37], v[204:205], v[172:173], v[8:9]
	v_pk_fma_f32 v[38:39], v[208:209], v[170:171], v[6:7]
	v_pk_mul_f32 v[42:43], v[34:35], v[36:37] op_sel_hi:[0,1]
	v_pk_mul_f32 v[36:37], v[34:35], v[38:39] op_sel_hi:[0,1]
	v_pk_fma_f32 v[38:39], v[204:205], v[168:169], v[4:5]
	v_cvt_pk_bf16_f32 v36, v36, v37
	v_cvt_pk_bf16_f32 v37, v42, v43
	s_nop 0
	v_pk_mul_f32 v[46:47], v[34:35], v[38:39] op_sel_hi:[0,1]
	v_pk_mul_f32 v[38:39], v[34:35], v[44:45] op_sel_hi:[0,1]
	v_cvt_pk_bf16_f32 v38, v38, v39
	v_cvt_pk_bf16_f32 v39, v46, v47
	ds_write_b128 v245, v[36:39] offset:256
; __device__ __forceinline__ unsigned cvt_pk_bf16(float lo, float hi) { unsigned r; asm("v_cvt_pk_bf16_f32 %0, %1, %2" : "=v"(r) : "v"(lo), "v"(hi)); return r; }
;     __device__ __forceinline__ void operator()(const f32x4 (&acc)[2][2][4][2], const pg8::Unit& u, int wr, int wc, int fr, int fq, LAS unsigned char* lds) const {
;     ...
; #pragma unroll
;         for (int ai = 0; ai < 2; ++ai)
; #pragma unroll
;             for (int m = 0; m < 4; ++m) { const int r = 128 * ai + 64 * wr + 16 * m + fr; if (r >= u.nvalid) continue;
; #pragma unroll
;                 for (int bj = 0; bj < 2; ++bj) { const int col = 256 * u.pn + 128 * bj + 32 * wc + 8 * fq;
;                     const f32x4 v0 = (acc[ai][bj][m][0] * dq + bv[bj][0]) * gw[ai][m], v1 = (acc[ai][bj][m][1] * dq + bv[bj][1]) * gw[ai][m];
;                     u32x4 o; o.x = cvt_pk_bf16(v0.x, v0.y); o.y = cvt_pk_bf16(v0.z, v0.w); o.z = cvt_pk_bf16(v1.x, v1.y); o.w = cvt_pk_bf16(v1.z, v1.w);
;                     *(u32x4*)(YK + (size_t)slot[ai][m] * D + col) = o; } }
;     }
.LBB0_2351:
	s_or_b64 exec, exec, s[4:5]
	s_waitcnt lgkmcnt(0)
	s_barrier
	ds_read_b128 v[182:185], v243
	ds_read_b128 v[186:189], v244
	ds_read_b32 v190, v246 offset:64
	ds_read_b32 v192, v246 offset:72
	s_waitcnt lgkmcnt(0)
	s_barrier
	v_add_u32_e32 v194, 16, v239
	v_cmp_lt_i32_e32 vcc, v194, v207
	s_and_saveexec_b64 s[4:5], vcc
	v_ashrrev_i32_e32 v191, 31, v190
	v_lshlrev_b64 v[190:191], 11, v[190:191]
	v_lshl_add_u64 v[190:191], v[240:241], 0, v[190:191]
	global_store_dwordx4 v[190:191], v[182:185], off
	s_or_b64 exec, exec, s[4:5]
	v_add_u32_e32 v194, 18, v239
	v_cmp_lt_i32_e32 vcc, v194, v207
	s_and_saveexec_b64 s[4:5], vcc
	v_ashrrev_i32_e32 v193, 31, v192
	v_lshlrev_b64 v[192:193], 11, v[192:193]
	v_lshl_add_u64 v[192:193], v[240:241], 0, v[192:193]
	global_store_dwordx4 v[192:193], v[186:189], off
	s_or_b64 exec, exec, s[4:5]
	v_add_u32_e32 v21, 32, v19
	v_cmp_lt_i32_e32 vcc, v21, v207
	s_and_saveexec_b64 s[4:5], vcc
	s_cbranch_execz .LBB0_2353
	v_mov_b32_e32 v205, v204
	s_waitcnt lgkmcnt(0)
	v_pk_fma_f32 v[38:39], v[208:209], v[162:163], v[14:15]
	v_mov_b32_e32 v32, v35
	v_pk_fma_f32 v[36:37], v[204:205], v[164:165], v[16:17]
	v_pk_mul_f32 v[34:35], v[32:33], v[38:39] op_sel_hi:[0,1]
	v_pk_fma_f32 v[38:39], v[204:205], v[160:161], v[12:13]
	v_pk_mul_f32 v[36:37], v[32:33], v[36:37] op_sel_hi:[0,1]
	v_pk_mul_f32 v[38:39], v[32:33], v[38:39] op_sel_hi:[0,1]
	v_cvt_pk_bf16_f32 v34, v34, v35
	v_cvt_pk_bf16_f32 v35, v36, v37
	v_cvt_pk_bf16_f32 v37, v38, v39
	v_ashrrev_i32_e32 v39, 31, v33
	v_mov_b32_e32 v38, v33
	v_lshlrev_b64 v[38:39], 11, v[38:39]
	v_lshl_add_u64 v[38:39], s[42:43], 0, v[38:39]
	v_pk_fma_f32 v[40:41], v[208:209], v[158:159], v[10:11]
	v_lshl_add_u64 v[38:39], v[22:23], 1, v[38:39]
	v_pk_mul_f32 v[40:41], v[32:33], v[40:41] op_sel_hi:[0,1]
	v_cvt_pk_bf16_f32 v36, v40, v41
	ds_write_b128 v245, v[34:37]
	v_pk_fma_f32 v[40:41], v[204:205], v[152:153], v[4:5]
	v_pk_fma_f32 v[42:43], v[208:209], v[150:151], v[2:3]
	v_pk_fma_f32 v[34:35], v[204:205], v[156:157], v[8:9]
	v_pk_fma_f32 v[36:37], v[208:209], v[154:155], v[6:7]
	v_pk_mul_f32 v[34:35], v[32:33], v[34:35] op_sel_hi:[0,1]
	v_pk_mul_f32 v[36:37], v[32:33], v[36:37] op_sel_hi:[0,1]
	v_pk_mul_f32 v[40:41], v[32:33], v[40:41] op_sel_hi:[0,1]
	v_pk_mul_f32 v[42:43], v[32:33], v[42:43] op_sel_hi:[0,1]
	v_cvt_pk_bf16_f32 v32, v36, v37
	v_cvt_pk_bf16_f32 v33, v34, v35
	v_cvt_pk_bf16_f32 v34, v42, v43
	v_cvt_pk_bf16_f32 v35, v40, v41
	ds_write_b128 v245, v[32:35] offset:256
.LBB0_2353:
	s_or_b64 exec, exec, s[4:5]
	s_waitcnt lgkmcnt(0)
	s_barrier
	ds_read_b128 v[182:185], v243
	ds_read_b128 v[186:189], v244
	ds_read_b32 v190, v246 offset:128
	ds_read_b32 v192, v246 offset:136
	s_waitcnt lgkmcnt(0)
	s_barrier
	v_add_u32_e32 v194, 32, v239
	v_cmp_lt_i32_e32 vcc, v194, v207
	s_and_saveexec_b64 s[4:5], vcc
	v_ashrrev_i32_e32 v191, 31, v190
	v_lshlrev_b64 v[190:191], 11, v[190:191]
	v_lshl_add_u64 v[190:191], v[240:241], 0, v[190:191]
	global_store_dwordx4 v[190:191], v[182:185], off
	s_or_b64 exec, exec, s[4:5]
	v_add_u32_e32 v194, 34, v239
	v_cmp_lt_i32_e32 vcc, v194, v207
	s_and_saveexec_b64 s[4:5], vcc
	v_ashrrev_i32_e32 v193, 31, v192
	v_lshlrev_b64 v[192:193], 11, v[192:193]
	v_lshl_add_u64 v[192:193], v[240:241], 0, v[192:193]
	global_store_dwordx4 v[192:193], v[186:189], off
	s_or_b64 exec, exec, s[4:5]
	v_add_u32_e32 v21, 48, v19
	v_cmp_lt_i32_e32 vcc, v21, v207
	s_and_saveexec_b64 s[4:5], vcc
	s_cbranch_execz .LBB0_2355
	v_mov_b32_e32 v205, v204
	s_waitcnt lgkmcnt(0)
	v_pk_fma_f32 v[32:33], v[204:205], v[148:149], v[16:17]
	v_pk_fma_f32 v[34:35], v[208:209], v[146:147], v[14:15]
	v_pk_mul_f32 v[36:37], v[30:31], v[32:33] op_sel_hi:[0,1]
	v_pk_mul_f32 v[32:33], v[30:31], v[34:35] op_sel_hi:[0,1]
	v_cvt_pk_bf16_f32 v32, v32, v33
	v_cvt_pk_bf16_f32 v33, v36, v37
	v_ashrrev_i32_e32 v37, 31, v28
	v_mov_b32_e32 v36, v28
	v_pk_fma_f32 v[34:35], v[204:205], v[144:145], v[12:13]
	v_pk_fma_f32 v[38:39], v[208:209], v[142:143], v[10:11]
	v_lshlrev_b64 v[36:37], 11, v[36:37]
	v_pk_mul_f32 v[40:41], v[30:31], v[34:35] op_sel_hi:[0,1]
	v_pk_mul_f32 v[34:35], v[30:31], v[38:39] op_sel_hi:[0,1]
	v_lshl_add_u64 v[36:37], s[42:43], 0, v[36:37]
	v_cvt_pk_bf16_f32 v34, v34, v35
	v_cvt_pk_bf16_f32 v35, v40, v41
	v_lshl_add_u64 v[36:37], v[22:23], 1, v[36:37]
	ds_write_b128 v245, v[32:35]
	v_pk_fma_f32 v[40:41], v[208:209], v[134:135], v[2:3]
	s_nop 0
	v_pk_fma_f32 v[32:33], v[204:205], v[140:141], v[8:9]
	v_pk_fma_f32 v[34:35], v[208:209], v[138:139], v[6:7]
	v_pk_mul_f32 v[38:39], v[30:31], v[32:33] op_sel_hi:[0,1]
	v_pk_mul_f32 v[32:33], v[30:31], v[34:35] op_sel_hi:[0,1]
	v_pk_fma_f32 v[34:35], v[204:205], v[136:137], v[4:5]
	v_cvt_pk_bf16_f32 v32, v32, v33
	v_cvt_pk_bf16_f32 v33, v38, v39
	s_nop 0
	v_pk_mul_f32 v[42:43], v[30:31], v[34:35] op_sel_hi:[0,1]
	v_pk_mul_f32 v[34:35], v[30:31], v[40:41] op_sel_hi:[0,1]
	v_cvt_pk_bf16_f32 v34, v34, v35
	v_cvt_pk_bf16_f32 v35, v42, v43
	ds_write_b128 v245, v[32:35] offset:256
; __device__ __forceinline__ unsigned cvt_pk_bf16(float lo, float hi) { unsigned r; asm("v_cvt_pk_bf16_f32 %0, %1, %2" : "=v"(r) : "v"(lo), "v"(hi)); return r; }
;     __device__ __forceinline__ void operator()(const f32x4 (&acc)[2][2][4][2], const pg8::Unit& u, int wr, int wc, int fr, int fq, LAS unsigned char* lds) const {
;     ...
; #pragma unroll
;         for (int ai = 0; ai < 2; ++ai)
; #pragma unroll
;             for (int m = 0; m < 4; ++m) { const int r = 128 * ai + 64 * wr + 16 * m + fr; if (r >= u.nvalid) continue;
; #pragma unroll
;                 for (int bj = 0; bj < 2; ++bj) { const int col = 256 * u.pn + 128 * bj + 32 * wc + 8 * fq;
;                     const f32x4 v0 = (acc[ai][bj][m][0] * dq + bv[bj][0]) * gw[ai][m], v1 = (acc[ai][bj][m][1] * dq + bv[bj][1]) * gw[ai][m];
;                     u32x4 o; o.x = cvt_pk_bf16(v0.x, v0.y); o.y = cvt_pk_bf16(v0.z, v0.w); o.z = cvt_pk_bf16(v1.x, v1.y); o.w = cvt_pk_bf16(v1.z, v1.w);
;                     *(u32x4*)(YK + (size_t)slot[ai][m] * D + col) = o; } }
;     }
.LBB0_2355:
	s_or_b64 exec, exec, s[4:5]
	s_waitcnt lgkmcnt(0)
	s_barrier
	ds_read_b128 v[182:185], v243
	ds_read_b128 v[186:189], v244
	ds_read_b32 v190, v246 offset:192
	ds_read_b32 v192, v246 offset:200
	s_waitcnt lgkmcnt(0)
	s_barrier
	v_add_u32_e32 v194, 48, v239
	v_cmp_lt_i32_e32 vcc, v194, v207
	s_and_saveexec_b64 s[4:5], vcc
	v_ashrrev_i32_e32 v191, 31, v190
	v_lshlrev_b64 v[190:191], 11, v[190:191]
	v_lshl_add_u64 v[190:191], v[240:241], 0, v[190:191]
	global_store_dwordx4 v[190:191], v[182:185], off
	s_or_b64 exec, exec, s[4:5]
	v_add_u32_e32 v194, 50, v239
	v_cmp_lt_i32_e32 vcc, v194, v207
	s_and_saveexec_b64 s[4:5], vcc
	v_ashrrev_i32_e32 v193, 31, v192
	v_lshlrev_b64 v[192:193], 11, v[192:193]
	v_lshl_add_u64 v[192:193], v[240:241], 0, v[192:193]
	global_store_dwordx4 v[192:193], v[186:189], off
	s_or_b64 exec, exec, s[4:5]
	v_add_u32_e32 v21, 0x80, v19
	v_cmp_lt_i32_e32 vcc, v21, v207
	s_and_saveexec_b64 s[4:5], vcc
	s_cbranch_execz .LBB0_2357
	v_mov_b32_e32 v205, v204
	s_waitcnt lgkmcnt(0)
	v_pk_fma_f32 v[34:35], v[208:209], v[130:131], v[14:15]
	v_mov_b32_e32 v28, v31
	v_pk_fma_f32 v[32:33], v[204:205], v[132:133], v[16:17]
	v_pk_mul_f32 v[30:31], v[28:29], v[34:35] op_sel_hi:[0,1]
	v_pk_fma_f32 v[34:35], v[204:205], v[128:129], v[12:13]
	v_pk_mul_f32 v[32:33], v[28:29], v[32:33] op_sel_hi:[0,1]
	v_pk_mul_f32 v[34:35], v[28:29], v[34:35] op_sel_hi:[0,1]
	v_cvt_pk_bf16_f32 v30, v30, v31
	v_cvt_pk_bf16_f32 v31, v32, v33
	v_cvt_pk_bf16_f32 v33, v34, v35
	v_ashrrev_i32_e32 v35, 31, v29
	v_mov_b32_e32 v34, v29
	v_lshlrev_b64 v[34:35], 11, v[34:35]
	v_lshl_add_u64 v[34:35], s[42:43], 0, v[34:35]
	v_pk_fma_f32 v[36:37], v[208:209], v[126:127], v[10:11]
	v_lshl_add_u64 v[34:35], v[22:23], 1, v[34:35]
	v_pk_mul_f32 v[36:37], v[28:29], v[36:37] op_sel_hi:[0,1]
	v_cvt_pk_bf16_f32 v32, v36, v37
	ds_write_b128 v245, v[30:33]
	v_pk_fma_f32 v[36:37], v[204:205], v[120:121], v[4:5]
	v_pk_fma_f32 v[38:39], v[208:209], v[118:119], v[2:3]
	v_pk_fma_f32 v[30:31], v[204:205], v[124:125], v[8:9]
	v_pk_fma_f32 v[32:33], v[208:209], v[122:123], v[6:7]
	v_pk_mul_f32 v[30:31], v[28:29], v[30:31] op_sel_hi:[0,1]
	v_pk_mul_f32 v[32:33], v[28:29], v[32:33] op_sel_hi:[0,1]
	v_pk_mul_f32 v[36:37], v[28:29], v[36:37] op_sel_hi:[0,1]
	v_pk_mul_f32 v[38:39], v[28:29], v[38:39] op_sel_hi:[0,1]
	v_cvt_pk_bf16_f32 v28, v32, v33
	v_cvt_pk_bf16_f32 v29, v30, v31
	v_cvt_pk_bf16_f32 v30, v38, v39
	v_cvt_pk_bf16_f32 v31, v36, v37
	ds_write_b128 v245, v[28:31] offset:256
.LBB0_2357:
	s_or_b64 exec, exec, s[4:5]
	s_waitcnt lgkmcnt(0)
	s_barrier
	ds_read_b128 v[182:185], v243
	ds_read_b128 v[186:189], v244
	ds_read_b32 v190, v246 offset:512
	ds_read_b32 v192, v246 offset:520
	s_waitcnt lgkmcnt(0)
	s_barrier
	v_add_u32_e32 v194, 0x80, v239
	v_cmp_lt_i32_e32 vcc, v194, v207
	s_and_saveexec_b64 s[4:5], vcc
	v_ashrrev_i32_e32 v191, 31, v190
	v_lshlrev_b64 v[190:191], 11, v[190:191]
	v_lshl_add_u64 v[190:191], v[240:241], 0, v[190:191]
	global_store_dwordx4 v[190:191], v[182:185], off
	s_or_b64 exec, exec, s[4:5]
	v_add_u32_e32 v194, 0x82, v239
	v_cmp_lt_i32_e32 vcc, v194, v207
	s_and_saveexec_b64 s[4:5], vcc
	v_ashrrev_i32_e32 v193, 31, v192
	v_lshlrev_b64 v[192:193], 11, v[192:193]
	v_lshl_add_u64 v[192:193], v[240:241], 0, v[192:193]
	global_store_dwordx4 v[192:193], v[186:189], off
	s_or_b64 exec, exec, s[4:5]
	v_add_u32_e32 v21, 0x90, v19
	v_cmp_lt_i32_e32 vcc, v21, v207
	s_and_saveexec_b64 s[4:5], vcc
	s_cbranch_execz .LBB0_2359
	v_mov_b32_e32 v205, v204
	s_waitcnt lgkmcnt(0)
	v_pk_fma_f32 v[28:29], v[204:205], v[116:117], v[16:17]
	v_pk_fma_f32 v[30:31], v[208:209], v[114:115], v[14:15]
	v_pk_mul_f32 v[32:33], v[26:27], v[28:29] op_sel_hi:[0,1]
	v_pk_mul_f32 v[28:29], v[26:27], v[30:31] op_sel_hi:[0,1]
	v_cvt_pk_bf16_f32 v28, v28, v29
	v_cvt_pk_bf16_f32 v29, v32, v33
	v_ashrrev_i32_e32 v33, 31, v24
	v_mov_b32_e32 v32, v24
	v_pk_fma_f32 v[30:31], v[204:205], v[112:113], v[12:13]
	v_pk_fma_f32 v[34:35], v[208:209], v[110:111], v[10:11]
	v_lshlrev_b64 v[32:33], 11, v[32:33]
	v_pk_mul_f32 v[36:37], v[26:27], v[30:31] op_sel_hi:[0,1]
	v_pk_mul_f32 v[30:31], v[26:27], v[34:35] op_sel_hi:[0,1]
	v_lshl_add_u64 v[32:33], s[42:43], 0, v[32:33]
	v_cvt_pk_bf16_f32 v30, v30, v31
	v_cvt_pk_bf16_f32 v31, v36, v37
	v_lshl_add_u64 v[32:33], v[22:23], 1, v[32:33]
	ds_write_b128 v245, v[28:31]
	v_pk_fma_f32 v[36:37], v[208:209], v[102:103], v[2:3]
	s_nop 0
	v_pk_fma_f32 v[28:29], v[204:205], v[108:109], v[8:9]
	v_pk_fma_f32 v[30:31], v[208:209], v[106:107], v[6:7]
	v_pk_mul_f32 v[34:35], v[26:27], v[28:29] op_sel_hi:[0,1]
	v_pk_mul_f32 v[28:29], v[26:27], v[30:31] op_sel_hi:[0,1]
	v_pk_fma_f32 v[30:31], v[204:205], v[104:105], v[4:5]
	v_cvt_pk_bf16_f32 v28, v28, v29
	v_cvt_pk_bf16_f32 v29, v34, v35
	s_nop 0
	v_pk_mul_f32 v[38:39], v[26:27], v[30:31] op_sel_hi:[0,1]
	v_pk_mul_f32 v[30:31], v[26:27], v[36:37] op_sel_hi:[0,1]
	v_cvt_pk_bf16_f32 v30, v30, v31
	v_cvt_pk_bf16_f32 v31, v38, v39
	ds_write_b128 v245, v[28:31] offset:256
; __device__ __forceinline__ unsigned cvt_pk_bf16(float lo, float hi) { unsigned r; asm("v_cvt_pk_bf16_f32 %0, %1, %2" : "=v"(r) : "v"(lo), "v"(hi)); return r; }
; #define PG8_BAR __builtin_amdgcn_s_barrier()
; template <bool FP8, class Epi, class Sched, class ARow, class BBase>
; __device__ __forceinline__ void gemm_phase(LAS unsigned char* lds, const void* Abase, const ARow& AR, const BBase& BB, const Sched& S, const Epi& E, int tid) {
;     ...
;         if (!has_next) break;
; #pragma unroll
;         for (int a = 0; a < 2; ++a)
; #pragma unroll
;             for (int b = 0; b < 2; ++b)
; #pragma unroll
;                 for (int m = 0; m < 4; ++m)
; #pragma unroll
;                     for (int n = 0; n < 2; ++n) acc[a][b][m][n] = (f32x4){0.f, 0.f, 0.f, 0.f};
;         cur = nxt; cB = nB; ++ui;
;         if (wr == 1) PG8_BAR;
;     __device__ __forceinline__ void operator()(const f32x4 (&acc)[2][2][4][2], const pg8::Unit& u, int wr, int wc, int fr, int fq, LAS unsigned char* lds) const {
;     ...
; #pragma unroll
;         for (int ai = 0; ai < 2; ++ai)
; #pragma unroll
;             for (int m = 0; m < 4; ++m) { const int r = 128 * ai + 64 * wr + 16 * m + fr; if (r >= u.nvalid) continue;
; #pragma unroll
;                 for (int bj = 0; bj < 2; ++bj) { const int col = 256 * u.pn + 128 * bj + 32 * wc + 8 * fq;
;                     const f32x4 v0 = (acc[ai][bj][m][0] * dq + bv[bj][0]) * gw[ai][m], v1 = (acc[ai][bj][m][1] * dq + bv[bj][1]) * gw[ai][m];
;                     u32x4 o; o.x = cvt_pk_bf16(v0.x, v0.y); o.y = cvt_pk_bf16(v0.z, v0.w); o.z = cvt_pk_bf16(v1.x, v1.y); o.w = cvt_pk_bf16(v1.z, v1.w);
;                     *(u32x4*)(YK + (size_t)slot[ai][m] * D + col) = o; } }
;     }
.LBB0_2359:
	s_or_b64 exec, exec, s[4:5]
	s_waitcnt lgkmcnt(0)
	s_barrier
	ds_read_b128 v[182:185], v243
	ds_read_b128 v[186:189], v244
	ds_read_b32 v190, v246 offset:576
	ds_read_b32 v192, v246 offset:584
	s_waitcnt lgkmcnt(0)
	s_barrier
	v_add_u32_e32 v194, 0x90, v239
	v_cmp_lt_i32_e32 vcc, v194, v207
	s_and_saveexec_b64 s[4:5], vcc
	v_ashrrev_i32_e32 v191, 31, v190
	v_lshlrev_b64 v[190:191], 11, v[190:191]
	v_lshl_add_u64 v[190:191], v[240:241], 0, v[190:191]
	global_store_dwordx4 v[190:191], v[182:185], off
	s_or_b64 exec, exec, s[4:5]
	v_add_u32_e32 v194, 0x92, v239
	v_cmp_lt_i32_e32 vcc, v194, v207
	s_and_saveexec_b64 s[4:5], vcc
	v_ashrrev_i32_e32 v193, 31, v192
	v_lshlrev_b64 v[192:193], 11, v[192:193]
	v_lshl_add_u64 v[192:193], v[240:241], 0, v[192:193]
	global_store_dwordx4 v[192:193], v[186:189], off
	s_or_b64 exec, exec, s[4:5]
	v_add_u32_e32 v21, 0xa0, v19
	v_cmp_lt_i32_e32 vcc, v21, v207
	s_and_saveexec_b64 s[4:5], vcc
	s_cbranch_execz .LBB0_2361
	v_mov_b32_e32 v205, v204
	s_waitcnt lgkmcnt(0)
	v_pk_fma_f32 v[30:31], v[208:209], v[98:99], v[14:15]
	v_mov_b32_e32 v24, v27
	v_pk_fma_f32 v[28:29], v[204:205], v[100:101], v[16:17]
	v_pk_mul_f32 v[26:27], v[24:25], v[30:31] op_sel_hi:[0,1]
	v_pk_fma_f32 v[30:31], v[204:205], v[96:97], v[12:13]
	v_pk_mul_f32 v[28:29], v[24:25], v[28:29] op_sel_hi:[0,1]
	v_pk_mul_f32 v[30:31], v[24:25], v[30:31] op_sel_hi:[0,1]
	v_cvt_pk_bf16_f32 v26, v26, v27
	v_cvt_pk_bf16_f32 v27, v28, v29
	v_cvt_pk_bf16_f32 v29, v30, v31
	v_ashrrev_i32_e32 v31, 31, v25
	v_mov_b32_e32 v30, v25
	v_lshlrev_b64 v[30:31], 11, v[30:31]
	v_lshl_add_u64 v[30:31], s[42:43], 0, v[30:31]
	v_pk_fma_f32 v[32:33], v[208:209], v[94:95], v[10:11]
	v_lshl_add_u64 v[30:31], v[22:23], 1, v[30:31]
	v_pk_mul_f32 v[32:33], v[24:25], v[32:33] op_sel_hi:[0,1]
	v_cvt_pk_bf16_f32 v28, v32, v33
	ds_write_b128 v245, v[26:29]
	v_pk_fma_f32 v[32:33], v[204:205], v[88:89], v[4:5]
	v_pk_fma_f32 v[34:35], v[208:209], v[86:87], v[2:3]
	v_pk_fma_f32 v[26:27], v[204:205], v[92:93], v[8:9]
	v_pk_fma_f32 v[28:29], v[208:209], v[90:91], v[6:7]
	v_pk_mul_f32 v[26:27], v[24:25], v[26:27] op_sel_hi:[0,1]
	v_pk_mul_f32 v[28:29], v[24:25], v[28:29] op_sel_hi:[0,1]
	v_pk_mul_f32 v[32:33], v[24:25], v[32:33] op_sel_hi:[0,1]
	v_pk_mul_f32 v[34:35], v[24:25], v[34:35] op_sel_hi:[0,1]
	v_cvt_pk_bf16_f32 v24, v28, v29
	v_cvt_pk_bf16_f32 v25, v26, v27
	v_cvt_pk_bf16_f32 v26, v34, v35
	v_cvt_pk_bf16_f32 v27, v32, v33
	ds_write_b128 v245, v[24:27] offset:256
.LBB0_2361:
	s_or_b64 exec, exec, s[4:5]
	s_waitcnt lgkmcnt(0)
	s_barrier
	ds_read_b128 v[182:185], v243
	ds_read_b128 v[186:189], v244
	ds_read_b32 v190, v246 offset:640
	ds_read_b32 v192, v246 offset:648
	s_waitcnt lgkmcnt(0)
	s_barrier
	v_add_u32_e32 v194, 0xa0, v239
	v_cmp_lt_i32_e32 vcc, v194, v207
	s_and_saveexec_b64 s[4:5], vcc
	v_ashrrev_i32_e32 v191, 31, v190
	v_lshlrev_b64 v[190:191], 11, v[190:191]
	v_lshl_add_u64 v[190:191], v[240:241], 0, v[190:191]
	global_store_dwordx4 v[190:191], v[182:185], off
	s_or_b64 exec, exec, s[4:5]
	v_add_u32_e32 v194, 0xa2, v239
	v_cmp_lt_i32_e32 vcc, v194, v207
	s_and_saveexec_b64 s[4:5], vcc
	v_ashrrev_i32_e32 v193, 31, v192
	v_lshlrev_b64 v[192:193], 11, v[192:193]
	v_lshl_add_u64 v[192:193], v[240:241], 0, v[192:193]
	global_store_dwordx4 v[192:193], v[186:189], off
	s_or_b64 exec, exec, s[4:5]
	v_add_u32_e32 v19, 0xb0, v19
	v_cmp_lt_i32_e32 vcc, v19, v207
	s_and_saveexec_b64 s[4:5], vcc
	s_cbranch_execz .LBB0_2363
	v_mov_b32_e32 v205, v204
	s_waitcnt lgkmcnt(0)
	v_pk_fma_f32 v[14:15], v[208:209], v[82:83], v[14:15]
	v_pk_fma_f32 v[12:13], v[204:205], v[80:81], v[12:13]
	v_pk_mul_f32 v[14:15], v[18:19], v[14:15] op_sel_hi:[0,1]
	v_pk_fma_f32 v[10:11], v[208:209], v[78:79], v[10:11]
	v_ashrrev_i32_e32 v21, 31, v20
	v_pk_mul_f32 v[24:25], v[18:19], v[12:13] op_sel_hi:[0,1]
	v_pk_mul_f32 v[12:13], v[18:19], v[10:11] op_sel_hi:[0,1]
	v_cvt_pk_bf16_f32 v10, v14, v15
	v_lshlrev_b64 v[14:15], 11, v[20:21]
	v_pk_fma_f32 v[16:17], v[204:205], v[84:85], v[16:17]
	v_lshl_add_u64 v[14:15], s[42:43], 0, v[14:15]
	v_pk_mul_f32 v[16:17], v[18:19], v[16:17] op_sel_hi:[0,1]
	v_cvt_pk_bf16_f32 v11, v16, v17
	v_lshl_add_u64 v[14:15], v[22:23], 1, v[14:15]
	v_pk_fma_f32 v[4:5], v[204:205], v[72:73], v[4:5]
	v_pk_fma_f32 v[2:3], v[208:209], v[70:71], v[2:3]
	v_cvt_pk_bf16_f32 v12, v12, v13
	v_cvt_pk_bf16_f32 v13, v24, v25
	ds_write_b128 v245, v[10:13]
	v_pk_fma_f32 v[8:9], v[204:205], v[76:77], v[8:9]
	v_pk_fma_f32 v[6:7], v[208:209], v[74:75], v[6:7]
	v_pk_mul_f32 v[10:11], v[18:19], v[4:5] op_sel_hi:[0,1]
	v_pk_mul_f32 v[4:5], v[18:19], v[2:3] op_sel_hi:[0,1]
	v_pk_mul_f32 v[8:9], v[18:19], v[8:9] op_sel_hi:[0,1]
	v_pk_mul_f32 v[6:7], v[18:19], v[6:7] op_sel_hi:[0,1]
	v_cvt_pk_bf16_f32 v2, v6, v7
	v_cvt_pk_bf16_f32 v3, v8, v9
	v_cvt_pk_bf16_f32 v4, v4, v5
	v_cvt_pk_bf16_f32 v5, v10, v11
	ds_write_b128 v245, v[2:5] offset:256
.LBB0_2363:
	s_or_b64 exec, exec, s[4:5]
	s_waitcnt lgkmcnt(0)
	s_barrier
	ds_read_b128 v[182:185], v243
	ds_read_b128 v[186:189], v244
	ds_read_b32 v190, v246 offset:704
	ds_read_b32 v192, v246 offset:712
	s_waitcnt lgkmcnt(0)
	s_barrier
	v_add_u32_e32 v194, 0xb0, v239
	v_cmp_lt_i32_e32 vcc, v194, v207
	s_and_saveexec_b64 s[4:5], vcc
	v_ashrrev_i32_e32 v191, 31, v190
	v_lshlrev_b64 v[190:191], 11, v[190:191]
	v_lshl_add_u64 v[190:191], v[240:241], 0, v[190:191]
	global_store_dwordx4 v[190:191], v[182:185], off
	s_or_b64 exec, exec, s[4:5]
	v_add_u32_e32 v194, 0xb2, v239
	v_cmp_lt_i32_e32 vcc, v194, v207
	s_and_saveexec_b64 s[4:5], vcc
	v_ashrrev_i32_e32 v193, 31, v192
	v_lshlrev_b64 v[192:193], 11, v[192:193]
	v_lshl_add_u64 v[192:193], v[240:241], 0, v[192:193]
	global_store_dwordx4 v[192:193], v[186:189], off
	s_or_b64 exec, exec, s[4:5]
	s_and_b64 vcc, exec, s[0:1]
	s_mov_b64 s[0:1], -1
	s_cbranch_vccnz .LBB0_2325
	s_andn2_b64 vcc, exec, s[28:29]
	s_cbranch_vccnz .LBB0_2324
	s_barrier
	s_branch .LBB0_2324
